# P1 meta-row skinny GEMM loop: all 24 fragment loads issued before the 16 MFMAs (counted waits) instead of ~8 dependent round trips per trip
# speedup vs baseline: 1.0031x; 1.0031x over previous
; #define LAS __attribute__((address_space(3)))
; __global__ void __launch_bounds__(512, 2) fwd_mega(Params P_by_kernarg) {
;     ...
;             const int kq = wave & 3, item = vcu * 2 + (wave >> 2), pn = item >> 3, jg = item & 7, l15 = lane & 15, fq = lane >> 4;
;             const bf16_t* b0p = Win_t + ((size_t)(pn * 256 + jg * 16 + l15)) * DM + kq * 1024 + fq * 8; const bf16_t* b1p = b0p + (size_t)128 * DM;
;             const bf16_t* ap = Ubuf + ((size_t)(MX + l15)) * DM + kq * 1024 + fq * 8;
;             f32x4 c0 = (f32x4){0.f, 0.f, 0.f, 0.f}, c1 = c0;
; #pragma unroll 8
;             for (int ks = 0; ks < 32; ++ks) { const bf16x8 w0 = *(const bf16x8*)(b0p + ks * 32), w1 = *(const bf16x8*)(b1p + ks * 32), av = *(const bf16x8*)(ap + ks * 32);
;                 c0 = __builtin_amdgcn_mfma_f32_16x16x32_bf16(w0, av, c0, 0, 0, 0); c1 = __builtin_amdgcn_mfma_f32_16x16x32_bf16(w1, av, c1, 0, 0, 0); }
;             LAS f32x4* red = (LAS f32x4*)lds;
;             red[(wave * 2 + 0) * 64 + lane] = c0; red[(wave * 2 + 1) * 64 + lane] = c1;
;             __syncthreads();
;             if (kq == 0) {
; #pragma unroll
;                 for (int q = 1; q < 4; ++q) { c0 += red[((wave + q) * 2 + 0) * 64 + lane]; c1 += red[((wave + q) * 2 + 1) * 64 + lane]; }
;                 { const float rr = RS1[MX + l15]; c0 = c0 * rr; c1 = c1 * rr; }
;                 const int sect = pn >> 3, hd = pn & 7, pos = l15, j = jg * 16 + 4 * fq;
;                 bf16_t* buf = QKV + (size_t)sect * QKV_ELEMS + (size_t)pos * 2048 + hd * 256;
;                 if (sect < 2) { const int comp = j >> 6, i0 = j & 63;
;                     const f32x4 cs = *(const f32x4*)(cosT + pos * 64 + i0), sn = *(const f32x4*)(sinT + pos * 64 + i0);
;                     const f32x4 o1 = c0 * cs - c1 * sn, o2 = c1 * cs + c0 * sn;
;                     u32x2 w1, w2; w1.x = pk2(o1[0], o1[1]); w1.y = pk2(o1[2], o1[3]); w2.x = pk2(o2[0], o2[1]); w2.y = pk2(o2[2], o2[3]);
;                     bf16_t* p = buf + comp * 128 + i0;
;                     *(u32x2*)p = w1; *(u32x2*)(p + 64) = w2; *(u32x2*)(p + (size_t)TPAD * 2048) = w1; *(u32x2*)(p + (size_t)TPAD * 2048 + 64) = w2;
;                 } else { u32x2 w1, w2; w1.x = pk2(c0[0], c0[1]); w1.y = pk2(c0[2], c0[3]); w2.x = pk2(c1[0], c1[1]); w2.y = pk2(c1[2], c1[3]);
;                     bf16_t* p = buf + j;
.LBB0_113:
	v_lshl_add_u64 v[26:27], v[12:13], 0, s[2:3]
	v_lshl_add_u64 v[42:43], v[10:11], 0, s[2:3]
	v_add_co_u32_e32 v46, vcc, 0x1000000, v26
	s_add_u32 s2, s2, 0x200
	s_addc_u32 s3, s3, 0
	v_addc_co_u32_e32 v47, vcc, 0, v27, vcc
	v_add_co_u32_e32 v48, vcc, 0x1100000, v26
	s_nop 1
	v_addc_co_u32_e32 v49, vcc, 0, v27, vcc
	global_load_dwordx4 v[50:53], v[42:43], off offset:-256
	global_load_dwordx4 v[82:85], v[46:47], off
	global_load_dwordx4 v[114:117], v[48:49], off
	global_load_dwordx4 v[54:57], v[42:43], off offset:-192
	global_load_dwordx4 v[86:89], v[46:47], off offset:64
	global_load_dwordx4 v[118:121], v[48:49], off offset:64
	global_load_dwordx4 v[58:61], v[42:43], off offset:-128
	global_load_dwordx4 v[90:93], v[46:47], off offset:128
	global_load_dwordx4 v[122:125], v[48:49], off offset:128
	global_load_dwordx4 v[62:65], v[42:43], off offset:-64
	global_load_dwordx4 v[94:97], v[46:47], off offset:192
	global_load_dwordx4 v[126:129], v[48:49], off offset:192
	global_load_dwordx4 v[66:69], v[42:43], off
	global_load_dwordx4 v[98:101], v[46:47], off offset:256
	global_load_dwordx4 v[14:17], v[48:49], off offset:256
	global_load_dwordx4 v[70:73], v[42:43], off offset:64
	global_load_dwordx4 v[102:105], v[46:47], off offset:320
	global_load_dwordx4 v[18:21], v[48:49], off offset:320
	global_load_dwordx4 v[74:77], v[42:43], off offset:128
	global_load_dwordx4 v[106:109], v[46:47], off offset:384
	global_load_dwordx4 v[22:25], v[48:49], off offset:384
	global_load_dwordx4 v[78:81], v[42:43], off offset:192
	global_load_dwordx4 v[110:113], v[46:47], off offset:448
	global_load_dwordx4 v[28:31], v[48:49], off offset:448
	s_waitcnt vmcnt(21)
	v_mfma_f32_16x16x32_bf16 v[2:5], v[82:85], v[50:53], v[2:5]
	v_mfma_f32_16x16x32_bf16 v[6:9], v[114:117], v[50:53], v[6:9]
	s_waitcnt vmcnt(18)
	v_mfma_f32_16x16x32_bf16 v[2:5], v[86:89], v[54:57], v[2:5]
	v_mfma_f32_16x16x32_bf16 v[6:9], v[118:121], v[54:57], v[6:9]
	s_waitcnt vmcnt(15)
	v_mfma_f32_16x16x32_bf16 v[2:5], v[90:93], v[58:61], v[2:5]
	v_mfma_f32_16x16x32_bf16 v[6:9], v[122:125], v[58:61], v[6:9]
	s_waitcnt vmcnt(12)
	v_mfma_f32_16x16x32_bf16 v[2:5], v[94:97], v[62:65], v[2:5]
	v_mfma_f32_16x16x32_bf16 v[6:9], v[126:129], v[62:65], v[6:9]
	s_waitcnt vmcnt(9)
	v_mfma_f32_16x16x32_bf16 v[2:5], v[98:101], v[66:69], v[2:5]
	v_mfma_f32_16x16x32_bf16 v[6:9], v[14:17], v[66:69], v[6:9]
	s_waitcnt vmcnt(6)
	v_mfma_f32_16x16x32_bf16 v[2:5], v[102:105], v[70:73], v[2:5]
	v_mfma_f32_16x16x32_bf16 v[6:9], v[18:21], v[70:73], v[6:9]
	s_waitcnt vmcnt(3)
	v_mfma_f32_16x16x32_bf16 v[2:5], v[106:109], v[74:77], v[2:5]
	v_mfma_f32_16x16x32_bf16 v[6:9], v[22:25], v[74:77], v[6:9]
	s_waitcnt vmcnt(0)
	v_mfma_f32_16x16x32_bf16 v[2:5], v[110:113], v[78:81], v[2:5]
	v_mfma_f32_16x16x32_bf16 v[6:9], v[28:31], v[78:81], v[6:9]
	s_cmpk_eq_i32 s2, 0x800
	s_cbranch_scc0 .LBB0_113
	s_lshl_b32 s7, s66, 11
	s_and_b32 s2, s66, 3
	s_add_i32 s7, s7, 0
	s_mov_b32 s3, 0
	v_lshl_add_u32 v10, v196, 4, s7
	s_cmp_lg_u32 s2, 0
	ds_write_b128 v10, v[2:5]
	ds_write_b128 v10, v[6:9] offset:1024
	s_waitcnt lgkmcnt(0)
	s_barrier
	s_cbranch_scc1 .LBB0_119
	v_mov_b32_e32 v11, 0x8000
	v_lshl_or_b32 v12, v158, 2, v11
	v_mov_b32_e32 v13, 0
	v_lshl_add_u64 v[14:15], s[16:17], 0, v[12:13]
	s_mov_b32 s2, 0x18720000
	v_add_co_u32_e32 v14, vcc, s2, v14
	s_ashr_i32 s12, s6, 6
	s_nop 0
	v_addc_co_u32_e32 v15, vcc, 0, v15, vcc
	global_load_dword v40, v[14:15], off
	ds_read_b128 v[16:19], v10 offset:2048
	ds_read_b128 v[20:23], v10 offset:3072
	ds_read_b128 v[24:27], v10 offset:4096
	ds_read_b128 v[28:31], v10 offset:5120
	ds_read_b128 v[32:35], v10 offset:6144
	ds_read_b128 v[36:39], v10 offset:7168
	s_mul_i32 s10, s12, 0x2100000
	s_mul_hi_i32 s2, s12, 0x2100000
	s_add_u32 s10, s16, s10
	v_lshrrev_b32_e32 v10, 2, v196
	v_lshlrev_b32_e32 v12, 12, v158
	s_addc_u32 s11, s17, s2
	s_and_b32 s2, s5, 0x700
	s_waitcnt lgkmcnt(5)
	v_pk_add_f32 v[4:5], v[4:5], v[18:19]
	v_pk_add_f32 v[2:3], v[2:3], v[16:17]
	s_waitcnt lgkmcnt(4)
	v_pk_add_f32 v[8:9], v[8:9], v[22:23]
	v_pk_add_f32 v[6:7], v[6:7], v[20:21]
	v_and_or_b32 v14, v10, 12, s4
	v_lshl_add_u64 v[10:11], s[10:11], 0, v[12:13]
	s_lshl_b32 s2, s2, 1
	s_waitcnt lgkmcnt(3)
	v_pk_add_f32 v[4:5], v[4:5], v[26:27]
	v_pk_add_f32 v[2:3], v[2:3], v[24:25]
	s_waitcnt lgkmcnt(2)
	v_pk_add_f32 v[8:9], v[8:9], v[30:31]
	v_pk_add_f32 v[6:7], v[6:7], v[28:29]
	s_mov_b64 s[6:7], 0x1d200000
	v_lshl_add_u64 v[10:11], v[10:11], 0, s[2:3]
	s_waitcnt lgkmcnt(1)
	v_pk_add_f32 v[4:5], v[4:5], v[34:35]
	v_pk_add_f32 v[16:17], v[2:3], v[32:33]
	s_waitcnt lgkmcnt(0)
	v_pk_add_f32 v[18:19], v[8:9], v[38:39]
	v_pk_add_f32 v[6:7], v[6:7], v[36:37]
	s_cmp_gt_i32 s12, 1
	v_lshl_add_u64 v[10:11], v[10:11], 0, s[6:7]
	s_mov_b64 s[2:3], -1
	s_waitcnt vmcnt(0)
	v_pk_mul_f32 v[2:3], v[4:5], v[40:41] op_sel_hi:[1,0]
	v_pk_mul_f32 v[8:9], v[16:17], v[40:41] op_sel_hi:[1,0]
	v_pk_mul_f32 v[4:5], v[18:19], v[40:41] op_sel_hi:[1,0]
	v_pk_mul_f32 v[6:7], v[6:7], v[40:41] op_sel_hi:[1,0]
	s_cbranch_scc0 .LBB0_117
	v_lshlrev_b32_e32 v12, 1, v14
	v_cvt_pk_bf16_f32 v16, v8, v9
	v_cvt_pk_bf16_f32 v17, v2, v3
	v_lshl_add_u64 v[12:13], v[10:11], 0, v[12:13]
	v_cvt_pk_bf16_f32 v18, v6, v7
	v_cvt_pk_bf16_f32 v19, v4, v5
	global_store_dwordx2 v[12:13], v[16:17], off
	global_store_dwordx2 v[12:13], v[18:19], off offset:256
	v_add_co_u32_e32 v12, vcc, 0x1080000, v12
	s_mov_b64 s[2:3], 0
	s_nop 0
	v_addc_co_u32_e32 v13, vcc, 0, v13, vcc
	global_store_dwordx2 v[12:13], v[16:17], off
	global_store_dwordx2 v[12:13], v[18:19], off offset:256
